# GEMM tile-loop head: vmcnt(0) flush replaced by s_nop (same code size, so code placement is unchanged) in the first pool GEMM and first ffn_up
# speedup vs baseline: 1.0136x; 1.0136x over previous
; template <class Epi>
; __device__ __forceinline__ void gemm_phase(LAS unsigned char* lds, const Gemm g, const StaticOrder& S, const Epi& E) {
;     ...
;         const bool has_next = S.next(ui + 1, nxt);
;         const char* nA = has_next ? (const char*)g.A + (size_t)rowstart(nxt.pm) * rstepA + (size_t)nxt.pn * gstepA : cA; const char* nB = has_next ? (const char*)g.Bt + (size_t)nxt.pn * tstepB : cB;
;     ...
; #pragma unroll
;         for (int a = 0; a < 2; ++a)
; #pragma unroll
;             for (int b = 0; b < 2; ++b)
; #pragma unroll
;                 for (int m = 0; m < 4; ++m)
; #pragma unroll
;                     for (int n = 0; n < 2; ++n) acc[a][b][m][n] = (f32x4){0.f, 0.f, 0.f, 0.f};
.LBB0_149:
	s_lshl_b64 s[0:1], s[96:97], 17
	s_add_u32 s64, s12, s0
	s_addc_u32 s65, s13, s1
	s_and_b64 s[0:1], s[6:7], exec
	v_mov_b32_e32 v0, 0
	s_cselect_b32 s41, s65, s9
	s_cselect_b32 s61, s64, s8
	s_mov_b32 s42, 0
	s_mov_b64 s[0:1], -1
	s_mov_b64 s[36:37], 0
	s_waitcnt lgkmcnt(0)
	v_mov_b32_e32 v1, v0
	v_mov_b32_e32 v2, v0
	v_mov_b32_e32 v3, v0
	v_mov_b32_e32 v4, v0
	v_mov_b32_e32 v5, v0
	v_mov_b32_e32 v6, v0
	v_mov_b32_e32 v7, v0
	s_nop 0
	v_mov_b32_e32 v16, v0
	v_mov_b32_e32 v17, v0
	v_mov_b32_e32 v18, v0
	v_mov_b32_e32 v19, v0
	v_mov_b32_e32 v20, v0
	v_mov_b32_e32 v21, v0
	v_mov_b32_e32 v22, v0
	v_mov_b32_e32 v23, v0
	v_mov_b32_e32 v32, v0
	v_mov_b32_e32 v33, v0
	v_mov_b32_e32 v34, v0
	v_mov_b32_e32 v35, v0
	v_mov_b32_e32 v36, v0
	v_mov_b32_e32 v37, v0
	v_mov_b32_e32 v38, v0
	v_mov_b32_e32 v39, v0
	v_mov_b32_e32 v80, v0
	v_mov_b32_e32 v81, v0
	v_mov_b32_e32 v82, v0
	v_mov_b32_e32 v83, v0
	v_mov_b32_e32 v84, v0
	v_mov_b32_e32 v85, v0
	v_mov_b32_e32 v86, v0
	v_mov_b32_e32 v87, v0
	v_mov_b32_e32 v8, v0
	v_mov_b32_e32 v9, v0
	v_mov_b32_e32 v10, v0
	v_mov_b32_e32 v11, v0
	v_mov_b32_e32 v12, v0
	v_mov_b32_e32 v13, v0
	v_mov_b32_e32 v14, v0
	v_mov_b32_e32 v15, v0
	v_mov_b32_e32 v24, v0
	v_mov_b32_e32 v25, v0
	v_mov_b32_e32 v26, v0
	v_mov_b32_e32 v27, v0
	v_mov_b32_e32 v28, v0
	v_mov_b32_e32 v29, v0
	v_mov_b32_e32 v30, v0
	v_mov_b32_e32 v31, v0
	v_mov_b32_e32 v56, v0
	v_mov_b32_e32 v57, v0
	v_mov_b32_e32 v58, v0
	v_mov_b32_e32 v59, v0
	v_mov_b32_e32 v64, v0
	v_mov_b32_e32 v65, v0
	v_mov_b32_e32 v66, v0
	v_mov_b32_e32 v67, v0
	v_mov_b32_e32 v88, v0
	v_mov_b32_e32 v89, v0
	v_mov_b32_e32 v90, v0
	v_mov_b32_e32 v91, v0
	v_mov_b32_e32 v92, v0
	v_mov_b32_e32 v93, v0
	v_mov_b32_e32 v94, v0
	v_mov_b32_e32 v95, v0
	v_mov_b32_e32 v96, v0
	v_mov_b32_e32 v97, v0
	v_mov_b32_e32 v98, v0
	v_mov_b32_e32 v99, v0
	v_mov_b32_e32 v100, v0
	v_mov_b32_e32 v101, v0
	v_mov_b32_e32 v102, v0
	v_mov_b32_e32 v103, v0
	v_mov_b32_e32 v112, v0
	v_mov_b32_e32 v113, v0
	v_mov_b32_e32 v114, v0
	v_mov_b32_e32 v115, v0
	v_mov_b32_e32 v116, v0
	v_mov_b32_e32 v117, v0
	v_mov_b32_e32 v118, v0
	v_mov_b32_e32 v119, v0
	v_mov_b32_e32 v128, v0
	v_mov_b32_e32 v129, v0
	v_mov_b32_e32 v130, v0
	v_mov_b32_e32 v131, v0
	v_mov_b32_e32 v132, v0
	v_mov_b32_e32 v133, v0
	v_mov_b32_e32 v134, v0
	v_mov_b32_e32 v135, v0
	v_mov_b32_e32 v144, v0
	v_mov_b32_e32 v145, v0
	v_mov_b32_e32 v146, v0
	v_mov_b32_e32 v147, v0
	v_mov_b32_e32 v148, v0
	v_mov_b32_e32 v149, v0
	v_mov_b32_e32 v150, v0
	v_mov_b32_e32 v151, v0
	v_mov_b32_e32 v104, v0
	v_mov_b32_e32 v105, v0
	v_mov_b32_e32 v106, v0
	v_mov_b32_e32 v107, v0
	v_mov_b32_e32 v108, v0
	v_mov_b32_e32 v109, v0
	v_mov_b32_e32 v110, v0
	v_mov_b32_e32 v111, v0
	v_mov_b32_e32 v120, v0
	v_mov_b32_e32 v121, v0
	v_mov_b32_e32 v122, v0
	v_mov_b32_e32 v123, v0
	v_mov_b32_e32 v124, v0
	v_mov_b32_e32 v125, v0
	v_mov_b32_e32 v126, v0
	v_mov_b32_e32 v127, v0
	v_mov_b32_e32 v136, v0
	v_mov_b32_e32 v137, v0
	v_mov_b32_e32 v138, v0
	v_mov_b32_e32 v139, v0
	v_mov_b32_e32 v140, v0
	v_mov_b32_e32 v141, v0
	v_mov_b32_e32 v142, v0
	v_mov_b32_e32 v143, v0
	v_mov_b32_e32 v152, v0
	v_mov_b32_e32 v153, v0
	v_mov_b32_e32 v154, v0
	v_mov_b32_e32 v155, v0
	v_mov_b32_e32 v156, v0
	v_mov_b32_e32 v157, v0
	v_mov_b32_e32 v158, v0
	v_mov_b32_e32 v159, v0

; template <class Epi>
; __device__ __forceinline__ void gemm_phase(LAS unsigned char* lds, const Gemm g, const StaticOrder& S, const Epi& E) {
;     ...
;         const bool has_next = S.next(ui + 1, nxt);
;         const char* nA = has_next ? (const char*)g.A + (size_t)rowstart(nxt.pm) * rstepA + (size_t)nxt.pn * gstepA : cA; const char* nB = has_next ? (const char*)g.Bt + (size_t)nxt.pn * tstepB : cB;
;     ...
; #pragma unroll
;         for (int a = 0; a < 2; ++a)
; #pragma unroll
;             for (int b = 0; b < 2; ++b)
; #pragma unroll
;                 for (int m = 0; m < 4; ++m)
; #pragma unroll
;                     for (int n = 0; n < 2; ++n) acc[a][b][m][n] = (f32x4){0.f, 0.f, 0.f, 0.f};
.LBB0_254:
	s_ashr_i32 s17, s16, 31
	s_lshl_b64 s[28:29], s[16:17], 19
	s_add_u32 s28, s84, s28
	s_addc_u32 s29, s85, s29
	s_and_b64 s[0:1], s[0:1], exec
	s_cselect_b32 s7, s29, s37
	s_cselect_b32 s17, s28, s36
	s_add_u32 s0, s38, 0x40080
	s_addc_u32 s1, s39, 0
	s_add_u32 s59, s36, 0x100
	v_mov_b32_e32 v0, 0
	s_addc_u32 s60, s37, 0
	s_mov_b32 s61, -2
	v_mov_b32_e32 v1, v0
	v_mov_b32_e32 v2, v0
	v_mov_b32_e32 v3, v0
	v_mov_b32_e32 v8, v0
	v_mov_b32_e32 v9, v0
	v_mov_b32_e32 v10, v0
	v_mov_b32_e32 v11, v0
	s_nop 0
	v_mov_b32_e32 v16, v0
	v_mov_b32_e32 v17, v0
	v_mov_b32_e32 v18, v0
	v_mov_b32_e32 v19, v0
	v_mov_b32_e32 v24, v0
	v_mov_b32_e32 v25, v0
	v_mov_b32_e32 v26, v0
	v_mov_b32_e32 v27, v0
	v_mov_b32_e32 v32, v0
	v_mov_b32_e32 v33, v0
	v_mov_b32_e32 v34, v0
	v_mov_b32_e32 v35, v0
	v_mov_b32_e32 v40, v0
	v_mov_b32_e32 v41, v0
	v_mov_b32_e32 v42, v0
	v_mov_b32_e32 v43, v0
	v_mov_b32_e32 v48, v0
	v_mov_b32_e32 v49, v0
	v_mov_b32_e32 v50, v0
	v_mov_b32_e32 v51, v0
	v_mov_b32_e32 v56, v0
	v_mov_b32_e32 v57, v0
	v_mov_b32_e32 v58, v0
	v_mov_b32_e32 v59, v0
	v_mov_b32_e32 v4, v0
	v_mov_b32_e32 v5, v0
	v_mov_b32_e32 v6, v0
	v_mov_b32_e32 v7, v0
	v_mov_b32_e32 v12, v0
	v_mov_b32_e32 v13, v0
	v_mov_b32_e32 v14, v0
	v_mov_b32_e32 v15, v0
	v_mov_b32_e32 v20, v0
	v_mov_b32_e32 v21, v0
	v_mov_b32_e32 v22, v0
	v_mov_b32_e32 v23, v0
	v_mov_b32_e32 v28, v0
	v_mov_b32_e32 v29, v0
	v_mov_b32_e32 v30, v0
	v_mov_b32_e32 v31, v0
	v_mov_b32_e32 v36, v0
	v_mov_b32_e32 v37, v0
	v_mov_b32_e32 v38, v0
	v_mov_b32_e32 v39, v0
	v_mov_b32_e32 v44, v0
	v_mov_b32_e32 v45, v0
	v_mov_b32_e32 v46, v0
	v_mov_b32_e32 v47, v0
	v_mov_b32_e32 v52, v0
	v_mov_b32_e32 v53, v0
	v_mov_b32_e32 v54, v0
	v_mov_b32_e32 v55, v0
	v_mov_b32_e32 v60, v0
	v_mov_b32_e32 v61, v0
	v_mov_b32_e32 v62, v0
	v_mov_b32_e32 v63, v0
	v_mov_b32_e32 v64, v0
	v_mov_b32_e32 v65, v0
	v_mov_b32_e32 v66, v0
	v_mov_b32_e32 v67, v0
	v_mov_b32_e32 v72, v0
	v_mov_b32_e32 v73, v0
	v_mov_b32_e32 v74, v0
	v_mov_b32_e32 v75, v0
	v_mov_b32_e32 v80, v0
	v_mov_b32_e32 v81, v0
	v_mov_b32_e32 v82, v0
	v_mov_b32_e32 v83, v0
	v_mov_b32_e32 v88, v0
	v_mov_b32_e32 v89, v0
	v_mov_b32_e32 v90, v0
	v_mov_b32_e32 v91, v0
	v_mov_b32_e32 v96, v0
	v_mov_b32_e32 v97, v0
	v_mov_b32_e32 v98, v0
	v_mov_b32_e32 v99, v0
	v_mov_b32_e32 v104, v0
	v_mov_b32_e32 v105, v0
	v_mov_b32_e32 v106, v0
	v_mov_b32_e32 v107, v0
	v_mov_b32_e32 v112, v0
	v_mov_b32_e32 v113, v0
	v_mov_b32_e32 v114, v0
	v_mov_b32_e32 v115, v0
	v_mov_b32_e32 v120, v0
	v_mov_b32_e32 v121, v0
	v_mov_b32_e32 v122, v0
	v_mov_b32_e32 v123, v0
	v_mov_b32_e32 v68, v0
	v_mov_b32_e32 v69, v0
	v_mov_b32_e32 v70, v0
	v_mov_b32_e32 v71, v0
	v_mov_b32_e32 v76, v0
	v_mov_b32_e32 v77, v0
	v_mov_b32_e32 v78, v0
	v_mov_b32_e32 v79, v0
	v_mov_b32_e32 v84, v0
	v_mov_b32_e32 v85, v0
	v_mov_b32_e32 v86, v0
	v_mov_b32_e32 v87, v0
	v_mov_b32_e32 v92, v0
	v_mov_b32_e32 v93, v0
	v_mov_b32_e32 v94, v0
	v_mov_b32_e32 v95, v0
	v_mov_b32_e32 v100, v0
	v_mov_b32_e32 v101, v0
	v_mov_b32_e32 v102, v0
	v_mov_b32_e32 v103, v0
	v_mov_b32_e32 v108, v0
	v_mov_b32_e32 v109, v0
	v_mov_b32_e32 v110, v0
	v_mov_b32_e32 v111, v0
	v_mov_b32_e32 v116, v0
	v_mov_b32_e32 v117, v0
	v_mov_b32_e32 v118, v0
	v_mov_b32_e32 v119, v0
	v_mov_b32_e32 v124, v0
	v_mov_b32_e32 v125, v0
	v_mov_b32_e32 v126, v0
	v_mov_b32_e32 v127, v0
